# first K iteration of non-first tiles: stage waits vmcnt(8+S) so the previous epilogue's S write-through stores need not be acked yet
# speedup vs baseline: 1.0025x; 1.0002x over previous
.LBB0_287:
	s_ashr_i32 s21, s20, 31
	s_lshl_b64 s[22:23], s[20:21], 19
	s_add_u32 s22, s80, s22
	s_addc_u32 s23, s81, s23
	s_and_b64 s[24:25], s[6:7], exec
	s_cselect_b32 s21, s23, s29
	s_cselect_b32 s36, s22, s28
	s_ashr_i32 s19, s18, 31
	s_lshl_b64 s[24:25], s[18:19], 19
	s_add_u32 s24, s40, s24
	s_addc_u32 s25, s41, s25
	s_and_b64 s[34:35], s[6:7], exec
	s_cselect_b32 s19, s25, s31
	s_cselect_b32 s37, s24, s30
	s_add_u32 s38, s30, 0x100
	s_addc_u32 s39, s31, 0
	s_add_u32 s28, s28, 0x40080
	s_addc_u32 s29, s29, 0
	s_mov_b32 s55, -2
	s_add_u32 s30, s28, 0xfffc0080
	s_addc_u32 s31, s29, -1
	s_add_i32 s56, 0, 0x10000
	s_cmp_eq_u32 s55, 12
	s_cselect_b32 s35, s21, s31
	s_cselect_b32 s34, s36, s30
	s_cselect_b32 s31, s19, s39
	s_cselect_b32 s30, s37, s38
	s_add_i32 s58, 0, 0x14000
	v_add_u32_e32 v166, s56, v147
	v_add_u32_e32 v182, s58, v147
	ds_read_b128 v[142:145], v166
	ds_read_b128 v[158:161], v166 offset:1024
	ds_read_b128 v[162:165], v166 offset:2048
	ds_read_b128 v[166:169], v166 offset:3072
	ds_read_b128 v[170:173], v182
	ds_read_b128 v[174:177], v182 offset:1024
	ds_read_b128 v[178:181], v182 offset:2048
	ds_read_b128 v[182:185], v182 offset:3072
	v_lshl_add_u64 v[224:225], s[28:29], 0, v[140:141]
	s_add_i32 m0, s44, 0xc000
	ds_read_b128 v[186:189], v157
	ds_read_b128 v[190:193], v157 offset:1024
	ds_read_b128 v[194:197], v157 offset:2048
	ds_read_b128 v[198:201], v157 offset:3072
	ds_read_b128 v[202:205], v157 offset:4096
	ds_read_b128 v[206:209], v157 offset:5120
	ds_read_b128 v[220:223], v157 offset:6144
	ds_read_b128 v[236:239], v157 offset:7168
	global_load_lds_dwordx4 v[224:225], off
	v_lshl_add_u64 v[224:225], s[28:29], 0, v[138:139]
	s_add_i32 m0, s44, 0xe000
	s_nop 0
	global_load_lds_dwordx4 v[224:225], off
	s_nop 0
	s_nop 0
	s_nop 0
	s_nop 0
	s_nop 0
	s_nop 0
	s_nop 0
	s_nop 0
	s_nop 0
	s_nop 0
	s_nop 0
	s_nop 0
	s_nop 0
	s_nop 0
	s_nop 0
	s_cmp_eq_u32 s9, 0
	s_cbranch_scc1 .Lkq_fw0
	s_waitcnt vmcnt(24)
	s_branch .Lkq_fj0

.Lkq_fj0:
	s_waitcnt lgkmcnt(0)
	s_barrier
	s_waitcnt lgkmcnt(0)
	v_mfma_f32_16x16x32_bf16 v[126:129], v[142:145], v[186:189], 0
	v_mfma_f32_16x16x32_bf16 v[122:125], v[162:165], v[186:189], 0
	v_mfma_f32_16x16x32_bf16 v[110:113], v[142:145], v[194:197], 0
	v_mfma_f32_16x16x32_bf16 v[106:109], v[162:165], v[194:197], 0
	v_mfma_f32_16x16x32_bf16 v[94:97], v[142:145], v[202:205], 0
	v_mfma_f32_16x16x32_bf16 v[90:93], v[162:165], v[202:205], 0
	v_mfma_f32_16x16x32_bf16 v[78:81], v[142:145], v[220:223], 0
	v_mfma_f32_16x16x32_bf16 v[74:77], v[162:165], v[220:223], 0
	v_mfma_f32_16x16x32_bf16 v[126:129], v[158:161], v[190:193], v[126:129]
	v_mfma_f32_16x16x32_bf16 v[122:125], v[166:169], v[190:193], v[122:125]
	v_mfma_f32_16x16x32_bf16 v[110:113], v[158:161], v[198:201], v[110:113]
	v_mfma_f32_16x16x32_bf16 v[106:109], v[166:169], v[198:201], v[106:109]
	v_mfma_f32_16x16x32_bf16 v[94:97], v[158:161], v[206:209], v[94:97]
	v_mfma_f32_16x16x32_bf16 v[90:93], v[166:169], v[206:209], v[90:93]
	v_mfma_f32_16x16x32_bf16 v[78:81], v[158:161], v[236:239], v[78:81]
	v_mfma_f32_16x16x32_bf16 v[74:77], v[166:169], v[236:239], v[74:77]
	v_mfma_f32_16x16x32_bf16 v[118:121], v[170:173], v[186:189], 0
	v_mfma_f32_16x16x32_bf16 v[114:117], v[178:181], v[186:189], 0
	v_mfma_f32_16x16x32_bf16 v[102:105], v[170:173], v[194:197], 0
	v_mfma_f32_16x16x32_bf16 v[98:101], v[178:181], v[194:197], 0
	v_mfma_f32_16x16x32_bf16 v[86:89], v[170:173], v[202:205], 0
	v_mfma_f32_16x16x32_bf16 v[82:85], v[178:181], v[202:205], 0
	v_mfma_f32_16x16x32_bf16 v[70:73], v[170:173], v[220:223], 0
	v_mfma_f32_16x16x32_bf16 v[66:69], v[178:181], v[220:223], 0
	v_mfma_f32_16x16x32_bf16 v[118:121], v[174:177], v[190:193], v[118:121]
	v_mfma_f32_16x16x32_bf16 v[114:117], v[182:185], v[190:193], v[114:117]
	v_mfma_f32_16x16x32_bf16 v[102:105], v[174:177], v[198:201], v[102:105]
	v_mfma_f32_16x16x32_bf16 v[98:101], v[182:185], v[198:201], v[98:101]
	v_mfma_f32_16x16x32_bf16 v[86:89], v[174:177], v[206:209], v[86:89]
	v_mfma_f32_16x16x32_bf16 v[82:85], v[182:185], v[206:209], v[82:85]
	v_mfma_f32_16x16x32_bf16 v[70:73], v[174:177], v[236:239], v[70:73]
	v_mfma_f32_16x16x32_bf16 v[66:69], v[182:185], v[236:239], v[66:69]
	s_barrier
	s_add_i32 s56, s56, s27
	v_lshl_add_u64 v[224:225], s[30:31], 0, v[132:133]
	s_mov_b32 m0, s56
	ds_read_b128 v[186:189], v157 offset:16384
	ds_read_b128 v[190:193], v157 offset:17408
	ds_read_b128 v[194:197], v157 offset:18432
	ds_read_b128 v[198:201], v157 offset:19456
	ds_read_b128 v[202:205], v157 offset:20480
	ds_read_b128 v[206:209], v157 offset:21504
	ds_read_b128 v[220:223], v157 offset:22528
	ds_read_b128 v[236:239], v157 offset:23552
	global_load_lds_dwordx4 v[224:225], off
	s_add_i32 m0, s56, 0x2000
	s_add_u32 s56, s30, 0x40000
	v_lshl_add_u64 v[230:231], s[30:31], 0, v[136:137]
	s_addc_u32 s57, s31, 0
	s_add_i32 s58, s58, s27
	global_load_lds_dwordx4 v[230:231], off
	v_lshl_add_u64 v[240:241], s[56:57], 0, v[132:133]
	s_mov_b32 m0, s58
	v_lshl_add_u64 v[242:243], s[34:35], 0, v[134:135]
	global_load_lds_dwordx4 v[240:241], off
	v_lshl_add_u64 v[240:241], s[56:57], 0, v[136:137]
	s_add_i32 m0, s58, 0x2000
	s_nop 0
	global_load_lds_dwordx4 v[240:241], off
	v_lshl_add_u64 v[240:241], s[34:35], 0, v[130:131]
	s_mov_b32 m0, s44
	s_nop 0
	global_load_lds_dwordx4 v[240:241], off
	s_mov_b32 m0, s45
	s_nop 0
	global_load_lds_dwordx4 v[242:243], off
	s_nop 0
	s_nop 0
	s_nop 0
	s_nop 0
	s_nop 0
	s_nop 0
	s_nop 0
	s_nop 0
	s_nop 0
	s_nop 0
	s_nop 0
	s_nop 0
	s_nop 0
	s_nop 0
	s_nop 0
	s_cmp_eq_u32 s9, 0
	s_cbranch_scc1 .Lkq_fw1
	s_waitcnt vmcnt(24)
	s_branch .Lkq_fj1

.Lkq_fj1:
	s_waitcnt lgkmcnt(0)
	s_barrier
	s_waitcnt lgkmcnt(0)
	v_mfma_f32_16x16x32_bf16 v[62:65], v[142:145], v[186:189], 0
	v_mfma_f32_16x16x32_bf16 v[58:61], v[162:165], v[186:189], 0
	v_mfma_f32_16x16x32_bf16 v[46:49], v[142:145], v[194:197], 0
	v_mfma_f32_16x16x32_bf16 v[42:45], v[162:165], v[194:197], 0
	v_mfma_f32_16x16x32_bf16 v[30:33], v[142:145], v[202:205], 0
	v_mfma_f32_16x16x32_bf16 v[26:29], v[162:165], v[202:205], 0
	v_mfma_f32_16x16x32_bf16 v[14:17], v[142:145], v[220:223], 0
	v_mfma_f32_16x16x32_bf16 v[10:13], v[162:165], v[220:223], 0
	v_mfma_f32_16x16x32_bf16 v[62:65], v[158:161], v[190:193], v[62:65]
	v_mfma_f32_16x16x32_bf16 v[58:61], v[166:169], v[190:193], v[58:61]
	v_mfma_f32_16x16x32_bf16 v[46:49], v[158:161], v[198:201], v[46:49]
	v_mfma_f32_16x16x32_bf16 v[42:45], v[166:169], v[198:201], v[42:45]
	v_mfma_f32_16x16x32_bf16 v[30:33], v[158:161], v[206:209], v[30:33]
	v_mfma_f32_16x16x32_bf16 v[26:29], v[166:169], v[206:209], v[26:29]
	v_mfma_f32_16x16x32_bf16 v[14:17], v[158:161], v[236:239], v[14:17]
	v_mfma_f32_16x16x32_bf16 v[10:13], v[166:169], v[236:239], v[10:13]
	v_mfma_f32_16x16x32_bf16 v[54:57], v[170:173], v[186:189], 0
	v_mfma_f32_16x16x32_bf16 v[50:53], v[178:181], v[186:189], 0
	v_mfma_f32_16x16x32_bf16 v[38:41], v[170:173], v[194:197], 0
	v_mfma_f32_16x16x32_bf16 v[34:37], v[178:181], v[194:197], 0
	v_mfma_f32_16x16x32_bf16 v[22:25], v[170:173], v[202:205], 0
	v_mfma_f32_16x16x32_bf16 v[18:21], v[178:181], v[202:205], 0
	v_mfma_f32_16x16x32_bf16 v[6:9], v[170:173], v[220:223], 0
	v_mfma_f32_16x16x32_bf16 v[2:5], v[178:181], v[220:223], 0
	v_mfma_f32_16x16x32_bf16 v[54:57], v[174:177], v[190:193], v[54:57]
	v_mfma_f32_16x16x32_bf16 v[50:53], v[182:185], v[190:193], v[50:53]
	v_mfma_f32_16x16x32_bf16 v[38:41], v[174:177], v[198:201], v[38:41]
	v_mfma_f32_16x16x32_bf16 v[34:37], v[182:185], v[198:201], v[34:37]
	v_mfma_f32_16x16x32_bf16 v[22:25], v[174:177], v[206:209], v[22:25]
	v_mfma_f32_16x16x32_bf16 v[18:21], v[182:185], v[206:209], v[18:21]
	v_mfma_f32_16x16x32_bf16 v[6:9], v[174:177], v[236:239], v[6:9]
	v_mfma_f32_16x16x32_bf16 v[2:5], v[182:185], v[236:239], v[2:5]
	s_barrier
	s_add_i32 s56, 0, 0x18000
	s_add_i32 s57, 0, 0x1c000
	v_add_u32_e32 v166, s56, v147
	v_add_u32_e32 v182, s57, v147
	ds_read_b128 v[142:145], v166
	ds_read_b128 v[158:161], v166 offset:1024
	ds_read_b128 v[162:165], v166 offset:2048
	ds_read_b128 v[166:169], v166 offset:3072
	ds_read_b128 v[170:173], v182
	ds_read_b128 v[174:177], v182 offset:1024
	ds_read_b128 v[178:181], v182 offset:2048
	ds_read_b128 v[182:185], v182 offset:3072
	s_add_u32 s34, s34, 0x40000
	s_addc_u32 s35, s35, 0
	s_mov_b32 m0, s43
	v_lshl_add_u64 v[244:245], s[34:35], 0, v[130:131]
	ds_read_b128 v[186:189], v157 offset:32768
	ds_read_b128 v[190:193], v157 offset:33792
	ds_read_b128 v[194:197], v157 offset:34816
	ds_read_b128 v[198:201], v157 offset:35840
	ds_read_b128 v[202:205], v157 offset:36864
	ds_read_b128 v[206:209], v157 offset:37888
	ds_read_b128 v[220:223], v157 offset:38912
	ds_read_b128 v[236:239], v157 offset:39936
	global_load_lds_dwordx4 v[244:245], off
	v_lshl_add_u64 v[244:245], s[34:35], 0, v[134:135]
	s_mov_b32 m0, s46
	s_nop 0
	global_load_lds_dwordx4 v[244:245], off
	s_nop 0
	s_nop 0
	s_nop 0
	s_nop 0
	s_nop 0
	s_nop 0
	s_nop 0
	s_waitcnt vmcnt(8)
	s_waitcnt lgkmcnt(0)
	s_barrier
	s_waitcnt lgkmcnt(0)
	v_mfma_f32_16x16x32_bf16 v[126:129], v[142:145], v[186:189], v[126:129]
	v_mfma_f32_16x16x32_bf16 v[122:125], v[162:165], v[186:189], v[122:125]
	v_mfma_f32_16x16x32_bf16 v[110:113], v[142:145], v[194:197], v[110:113]
	v_mfma_f32_16x16x32_bf16 v[106:109], v[162:165], v[194:197], v[106:109]
	v_mfma_f32_16x16x32_bf16 v[94:97], v[142:145], v[202:205], v[94:97]
	v_mfma_f32_16x16x32_bf16 v[90:93], v[162:165], v[202:205], v[90:93]
	v_mfma_f32_16x16x32_bf16 v[78:81], v[142:145], v[220:223], v[78:81]
	v_mfma_f32_16x16x32_bf16 v[74:77], v[162:165], v[220:223], v[74:77]
	v_mfma_f32_16x16x32_bf16 v[126:129], v[158:161], v[190:193], v[126:129]
	v_mfma_f32_16x16x32_bf16 v[122:125], v[166:169], v[190:193], v[122:125]
	v_mfma_f32_16x16x32_bf16 v[110:113], v[158:161], v[198:201], v[110:113]
	v_mfma_f32_16x16x32_bf16 v[106:109], v[166:169], v[198:201], v[106:109]
	v_mfma_f32_16x16x32_bf16 v[94:97], v[158:161], v[206:209], v[94:97]
	v_mfma_f32_16x16x32_bf16 v[90:93], v[166:169], v[206:209], v[90:93]
	v_mfma_f32_16x16x32_bf16 v[78:81], v[158:161], v[236:239], v[78:81]
	v_mfma_f32_16x16x32_bf16 v[74:77], v[166:169], v[236:239], v[74:77]
	v_mfma_f32_16x16x32_bf16 v[118:121], v[170:173], v[186:189], v[118:121]
	v_mfma_f32_16x16x32_bf16 v[114:117], v[178:181], v[186:189], v[114:117]
	v_mfma_f32_16x16x32_bf16 v[102:105], v[170:173], v[194:197], v[102:105]
	v_mfma_f32_16x16x32_bf16 v[98:101], v[178:181], v[194:197], v[98:101]
	v_mfma_f32_16x16x32_bf16 v[86:89], v[170:173], v[202:205], v[86:89]
	v_mfma_f32_16x16x32_bf16 v[82:85], v[178:181], v[202:205], v[82:85]
	v_mfma_f32_16x16x32_bf16 v[70:73], v[170:173], v[220:223], v[70:73]
	v_mfma_f32_16x16x32_bf16 v[66:69], v[178:181], v[220:223], v[66:69]
	v_mfma_f32_16x16x32_bf16 v[118:121], v[174:177], v[190:193], v[118:121]
	v_mfma_f32_16x16x32_bf16 v[114:117], v[182:185], v[190:193], v[114:117]
	v_mfma_f32_16x16x32_bf16 v[102:105], v[174:177], v[198:201], v[102:105]
	v_mfma_f32_16x16x32_bf16 v[98:101], v[182:185], v[198:201], v[98:101]
	v_mfma_f32_16x16x32_bf16 v[86:89], v[174:177], v[206:209], v[86:89]
	v_mfma_f32_16x16x32_bf16 v[82:85], v[182:185], v[206:209], v[82:85]
	v_mfma_f32_16x16x32_bf16 v[70:73], v[174:177], v[236:239], v[70:73]
	v_mfma_f32_16x16x32_bf16 v[66:69], v[182:185], v[236:239], v[66:69]
	s_barrier
	s_add_i32 s34, s56, s27
	v_lshl_add_u64 v[224:225], v[224:225], 0, s[96:97]
	s_mov_b32 m0, s34
	ds_read_b128 v[186:189], v157 offset:49152
	ds_read_b128 v[190:193], v157 offset:50176
	ds_read_b128 v[194:197], v157 offset:51200
	ds_read_b128 v[198:201], v157 offset:52224
	ds_read_b128 v[202:205], v157 offset:53248
	ds_read_b128 v[206:209], v157 offset:54272
	ds_read_b128 v[220:223], v157 offset:55296
	ds_read_b128 v[236:239], v157 offset:56320
	global_load_lds_dwordx4 v[224:225], off
	s_add_i32 m0, s34, 0x2000
	s_add_u32 s30, s30, 0x40080
	v_lshl_add_u64 v[224:225], v[230:231], 0, s[96:97]
	s_addc_u32 s31, s31, 0
	s_add_i32 s34, s57, s27
	global_load_lds_dwordx4 v[224:225], off
	v_lshl_add_u64 v[224:225], s[30:31], 0, v[132:133]
	s_mov_b32 m0, s34
	s_nop 0
	global_load_lds_dwordx4 v[224:225], off
	v_lshl_add_u64 v[224:225], s[30:31], 0, v[136:137]
	s_add_i32 m0, s34, 0x2000
	s_nop 0
	global_load_lds_dwordx4 v[224:225], off
	v_lshl_add_u64 v[224:225], v[240:241], 0, s[96:97]
	s_mov_b32 m0, s47
	s_nop 0
	global_load_lds_dwordx4 v[224:225], off
	v_lshl_add_u64 v[224:225], v[242:243], 0, s[96:97]
	s_mov_b32 m0, s48
	s_nop 0
	global_load_lds_dwordx4 v[224:225], off
	s_nop 0
	s_nop 0
	s_waitcnt vmcnt(8)
	s_waitcnt lgkmcnt(0)
	s_barrier
	s_waitcnt lgkmcnt(0)
	v_mfma_f32_16x16x32_bf16 v[62:65], v[142:145], v[186:189], v[62:65]
	v_mfma_f32_16x16x32_bf16 v[58:61], v[162:165], v[186:189], v[58:61]
	v_mfma_f32_16x16x32_bf16 v[46:49], v[142:145], v[194:197], v[46:49]
	v_mfma_f32_16x16x32_bf16 v[42:45], v[162:165], v[194:197], v[42:45]
	v_mfma_f32_16x16x32_bf16 v[30:33], v[142:145], v[202:205], v[30:33]
	v_mfma_f32_16x16x32_bf16 v[26:29], v[162:165], v[202:205], v[26:29]
	v_mfma_f32_16x16x32_bf16 v[14:17], v[142:145], v[220:223], v[14:17]
	v_mfma_f32_16x16x32_bf16 v[10:13], v[162:165], v[220:223], v[10:13]
	v_mfma_f32_16x16x32_bf16 v[62:65], v[158:161], v[190:193], v[62:65]
	v_mfma_f32_16x16x32_bf16 v[58:61], v[166:169], v[190:193], v[58:61]
	v_mfma_f32_16x16x32_bf16 v[46:49], v[158:161], v[198:201], v[46:49]
	v_mfma_f32_16x16x32_bf16 v[42:45], v[166:169], v[198:201], v[42:45]
	v_mfma_f32_16x16x32_bf16 v[30:33], v[158:161], v[206:209], v[30:33]
	v_mfma_f32_16x16x32_bf16 v[26:29], v[166:169], v[206:209], v[26:29]
	v_mfma_f32_16x16x32_bf16 v[14:17], v[158:161], v[236:239], v[14:17]
	v_mfma_f32_16x16x32_bf16 v[10:13], v[166:169], v[236:239], v[10:13]
	v_mfma_f32_16x16x32_bf16 v[54:57], v[170:173], v[186:189], v[54:57]
	v_mfma_f32_16x16x32_bf16 v[50:53], v[178:181], v[186:189], v[50:53]
	v_mfma_f32_16x16x32_bf16 v[38:41], v[170:173], v[194:197], v[38:41]
	v_mfma_f32_16x16x32_bf16 v[34:37], v[178:181], v[194:197], v[34:37]
	v_mfma_f32_16x16x32_bf16 v[22:25], v[170:173], v[202:205], v[22:25]
	v_mfma_f32_16x16x32_bf16 v[18:21], v[178:181], v[202:205], v[18:21]
	v_mfma_f32_16x16x32_bf16 v[6:9], v[170:173], v[220:223], v[6:9]
	v_mfma_f32_16x16x32_bf16 v[2:5], v[178:181], v[220:223], v[2:5]
	v_mfma_f32_16x16x32_bf16 v[54:57], v[174:177], v[190:193], v[54:57]
	v_mfma_f32_16x16x32_bf16 v[50:53], v[182:185], v[190:193], v[50:53]
	v_mfma_f32_16x16x32_bf16 v[38:41], v[174:177], v[198:201], v[38:41]
	v_mfma_f32_16x16x32_bf16 v[34:37], v[182:185], v[198:201], v[34:37]
	v_mfma_f32_16x16x32_bf16 v[22:25], v[174:177], v[206:209], v[22:25]
	v_mfma_f32_16x16x32_bf16 v[18:21], v[182:185], v[206:209], v[18:21]
	v_mfma_f32_16x16x32_bf16 v[6:9], v[174:177], v[236:239], v[6:9]
	v_mfma_f32_16x16x32_bf16 v[2:5], v[182:185], v[236:239], v[2:5]
	s_barrier
	s_add_i32 s55, s55, 2
	s_add_u32 s38, s38, 0x100
	s_addc_u32 s39, s39, 0
	s_add_u32 s28, s28, 0x100
	s_addc_u32 s29, s29, 0
	s_cmp_gt_u32 s55, 13

.LBB0_362:
	s_ashr_i32 s23, s22, 31
	s_lshl_b64 s[24:25], s[22:23], 19
	s_add_u32 s24, s80, s24
	s_addc_u32 s25, s81, s25
	s_and_b64 s[26:27], s[6:7], exec
	s_cselect_b32 s23, s25, s35
	s_cselect_b32 s39, s24, s34
	s_ashr_i32 s21, s20, 31
	s_lshl_b64 s[26:27], s[20:21], 19
	s_add_u32 s26, s45, s26
	s_addc_u32 s27, s46, s27
	s_and_b64 s[36:37], s[6:7], exec
	s_cselect_b32 s21, s27, s31
	s_cselect_b32 s40, s26, s30
	s_add_u32 s41, s30, 0x100
	s_addc_u32 s43, s31, 0
	s_add_u32 s30, s34, 0x40080
	s_addc_u32 s31, s35, 0
	s_mov_b32 s56, -2
	s_add_u32 s34, s30, 0xfffc0080
	s_addc_u32 s35, s31, -1
	s_add_i32 s57, 0, 0x10000
	s_cmp_eq_u32 s56, 12
	s_cselect_b32 s37, s23, s35
	s_cselect_b32 s36, s39, s34
	v_add_u32_e32 v146, s57, v155
	s_cselect_b32 s35, s21, s43
	s_cselect_b32 s34, s40, s41
	s_add_i32 s60, 0, 0x14000
	ds_read_b128 v[142:145], v146
	ds_read_b128 v[168:171], v146 offset:1024
	ds_read_b128 v[172:175], v146 offset:2048
	ds_read_b128 v[176:179], v146 offset:3072
	v_add_u32_e32 v146, s60, v155
	ds_read_b128 v[180:183], v146
	ds_read_b128 v[184:187], v146 offset:1024
	ds_read_b128 v[188:191], v146 offset:2048
	ds_read_b128 v[192:195], v146 offset:3072
	v_lshl_add_u64 v[146:147], s[30:31], 0, v[140:141]
	s_add_i32 m0, s48, 0xc000
	ds_read_b128 v[196:199], v157
	ds_read_b128 v[200:203], v157 offset:1024
	ds_read_b128 v[204:207], v157 offset:2048
	ds_read_b128 v[220:223], v157 offset:3072
	ds_read_b128 v[236:239], v157 offset:4096
	ds_read_b128 v[240:243], v157 offset:5120
	ds_read_b128 v[244:247], v157 offset:6144
	ds_read_b128 v[248:251], v157 offset:7168
	global_load_lds_dwordx4 v[146:147], off
	v_lshl_add_u64 v[146:147], s[30:31], 0, v[138:139]
	s_add_i32 m0, s48, 0xe000
	s_nop 0
	global_load_lds_dwordx4 v[146:147], off
	s_nop 0
	s_nop 0
	s_nop 0
	s_nop 0
	s_nop 0
	s_nop 0
	s_nop 0
	s_nop 0
	s_nop 0
	s_nop 0
	s_nop 0
	s_nop 0
	s_nop 0
	s_nop 0
	s_nop 0
	s_nop 0
	s_nop 0
	s_nop 0
	s_cmp_eq_u32 s38, 0
	s_cbranch_scc1 .Lsw_fw0
	s_waitcnt vmcnt(16)
	s_branch .Lsw_fj0

.Lsw_fj0:
	s_waitcnt lgkmcnt(0)
	s_barrier
	s_waitcnt lgkmcnt(0)
	v_mfma_f32_16x16x32_bf16 v[126:129], v[142:145], v[196:199], 0
	v_mfma_f32_16x16x32_bf16 v[118:121], v[172:175], v[196:199], 0
	v_mfma_f32_16x16x32_bf16 v[110:113], v[142:145], v[204:207], 0
	v_mfma_f32_16x16x32_bf16 v[102:105], v[172:175], v[204:207], 0
	v_mfma_f32_16x16x32_bf16 v[94:97], v[142:145], v[236:239], 0
	v_mfma_f32_16x16x32_bf16 v[86:89], v[172:175], v[236:239], 0
	v_mfma_f32_16x16x32_bf16 v[78:81], v[142:145], v[244:247], 0
	v_mfma_f32_16x16x32_bf16 v[70:73], v[172:175], v[244:247], 0
	v_mfma_f32_16x16x32_bf16 v[126:129], v[168:171], v[200:203], v[126:129]
	v_mfma_f32_16x16x32_bf16 v[118:121], v[176:179], v[200:203], v[118:121]
	v_mfma_f32_16x16x32_bf16 v[110:113], v[168:171], v[220:223], v[110:113]
	v_mfma_f32_16x16x32_bf16 v[102:105], v[176:179], v[220:223], v[102:105]
	v_mfma_f32_16x16x32_bf16 v[94:97], v[168:171], v[240:243], v[94:97]
	v_mfma_f32_16x16x32_bf16 v[86:89], v[176:179], v[240:243], v[86:89]
	v_mfma_f32_16x16x32_bf16 v[78:81], v[168:171], v[248:251], v[78:81]
	v_mfma_f32_16x16x32_bf16 v[70:73], v[176:179], v[248:251], v[70:73]
	v_mfma_f32_16x16x32_bf16 v[122:125], v[180:183], v[196:199], 0
	v_mfma_f32_16x16x32_bf16 v[114:117], v[188:191], v[196:199], 0
	v_mfma_f32_16x16x32_bf16 v[106:109], v[180:183], v[204:207], 0
	v_mfma_f32_16x16x32_bf16 v[98:101], v[188:191], v[204:207], 0
	v_mfma_f32_16x16x32_bf16 v[90:93], v[180:183], v[236:239], 0
	v_mfma_f32_16x16x32_bf16 v[82:85], v[188:191], v[236:239], 0
	v_mfma_f32_16x16x32_bf16 v[74:77], v[180:183], v[244:247], 0
	v_mfma_f32_16x16x32_bf16 v[66:69], v[188:191], v[244:247], 0
	v_mfma_f32_16x16x32_bf16 v[122:125], v[184:187], v[200:203], v[122:125]
	v_mfma_f32_16x16x32_bf16 v[114:117], v[192:195], v[200:203], v[114:117]
	v_mfma_f32_16x16x32_bf16 v[106:109], v[184:187], v[220:223], v[106:109]
	v_mfma_f32_16x16x32_bf16 v[98:101], v[192:195], v[220:223], v[98:101]
	v_mfma_f32_16x16x32_bf16 v[90:93], v[184:187], v[240:243], v[90:93]
	v_mfma_f32_16x16x32_bf16 v[82:85], v[192:195], v[240:243], v[82:85]
	v_mfma_f32_16x16x32_bf16 v[74:77], v[184:187], v[248:251], v[74:77]
	v_mfma_f32_16x16x32_bf16 v[66:69], v[192:195], v[248:251], v[66:69]
	s_barrier
	s_add_i32 s57, s57, s44
	v_lshl_add_u64 v[146:147], s[34:35], 0, v[134:135]
	s_mov_b32 m0, s57
	ds_read_b128 v[196:199], v157 offset:16384
	ds_read_b128 v[200:203], v157 offset:17408
	ds_read_b128 v[204:207], v157 offset:18432
	ds_read_b128 v[220:223], v157 offset:19456
	ds_read_b128 v[236:239], v157 offset:20480
	ds_read_b128 v[240:243], v157 offset:21504
	ds_read_b128 v[244:247], v157 offset:22528
	ds_read_b128 v[248:251], v157 offset:23552
	global_load_lds_dwordx4 v[146:147], off
	s_add_i32 m0, s57, 0x2000
	s_add_u32 s58, s34, 0x40000
	v_lshl_add_u64 v[208:209], s[34:35], 0, v[130:131]
	s_addc_u32 s59, s35, 0
	s_add_i32 s57, s60, s44
	global_load_lds_dwordx4 v[208:209], off
	v_lshl_add_u64 v[224:225], s[58:59], 0, v[134:135]
	s_mov_b32 m0, s57
	v_lshl_add_u64 v[230:231], s[36:37], 0, v[132:133]
	global_load_lds_dwordx4 v[224:225], off
	v_lshl_add_u64 v[224:225], s[58:59], 0, v[130:131]
	s_add_i32 m0, s57, 0x2000
	s_nop 0
	global_load_lds_dwordx4 v[224:225], off
	v_lshl_add_u64 v[224:225], s[36:37], 0, v[136:137]
	s_mov_b32 m0, s48
	s_nop 0
	global_load_lds_dwordx4 v[224:225], off
	s_mov_b32 m0, s49
	s_nop 0
	global_load_lds_dwordx4 v[230:231], off
	s_nop 0
	s_nop 0
	s_nop 0
	s_nop 0
	s_nop 0
	s_nop 0
	s_nop 0
	s_nop 0
	s_nop 0
	s_nop 0
	s_nop 0
	s_nop 0
	s_nop 0
	s_nop 0
	s_nop 0
	s_cmp_eq_u32 s38, 0
	s_cbranch_scc1 .Lsw_fw1
	s_waitcnt vmcnt(16)
	s_branch .Lsw_fj1

.Lsw_fj1:
	s_waitcnt lgkmcnt(0)
	s_barrier
	s_waitcnt lgkmcnt(0)
	v_mfma_f32_16x16x32_bf16 v[62:65], v[142:145], v[196:199], 0
	v_mfma_f32_16x16x32_bf16 v[54:57], v[172:175], v[196:199], 0
	v_mfma_f32_16x16x32_bf16 v[46:49], v[142:145], v[204:207], 0
	v_mfma_f32_16x16x32_bf16 v[38:41], v[172:175], v[204:207], 0
	v_mfma_f32_16x16x32_bf16 v[30:33], v[142:145], v[236:239], 0
	v_mfma_f32_16x16x32_bf16 v[22:25], v[172:175], v[236:239], 0
	v_mfma_f32_16x16x32_bf16 v[14:17], v[142:145], v[244:247], 0
	v_mfma_f32_16x16x32_bf16 v[6:9], v[172:175], v[244:247], 0
	v_mfma_f32_16x16x32_bf16 v[62:65], v[168:171], v[200:203], v[62:65]
	v_mfma_f32_16x16x32_bf16 v[54:57], v[176:179], v[200:203], v[54:57]
	v_mfma_f32_16x16x32_bf16 v[46:49], v[168:171], v[220:223], v[46:49]
	v_mfma_f32_16x16x32_bf16 v[38:41], v[176:179], v[220:223], v[38:41]
	v_mfma_f32_16x16x32_bf16 v[30:33], v[168:171], v[240:243], v[30:33]
	v_mfma_f32_16x16x32_bf16 v[22:25], v[176:179], v[240:243], v[22:25]
	v_mfma_f32_16x16x32_bf16 v[14:17], v[168:171], v[248:251], v[14:17]
	v_mfma_f32_16x16x32_bf16 v[6:9], v[176:179], v[248:251], v[6:9]
	v_mfma_f32_16x16x32_bf16 v[58:61], v[180:183], v[196:199], 0
	v_mfma_f32_16x16x32_bf16 v[50:53], v[188:191], v[196:199], 0
	v_mfma_f32_16x16x32_bf16 v[42:45], v[180:183], v[204:207], 0
	v_mfma_f32_16x16x32_bf16 v[34:37], v[188:191], v[204:207], 0
	v_mfma_f32_16x16x32_bf16 v[26:29], v[180:183], v[236:239], 0
	v_mfma_f32_16x16x32_bf16 v[18:21], v[188:191], v[236:239], 0
	v_mfma_f32_16x16x32_bf16 v[10:13], v[180:183], v[244:247], 0
	v_mfma_f32_16x16x32_bf16 v[2:5], v[188:191], v[244:247], 0
	v_mfma_f32_16x16x32_bf16 v[58:61], v[184:187], v[200:203], v[58:61]
	v_mfma_f32_16x16x32_bf16 v[50:53], v[192:195], v[200:203], v[50:53]
	v_mfma_f32_16x16x32_bf16 v[42:45], v[184:187], v[220:223], v[42:45]
	v_mfma_f32_16x16x32_bf16 v[34:37], v[192:195], v[220:223], v[34:37]
	v_mfma_f32_16x16x32_bf16 v[26:29], v[184:187], v[240:243], v[26:29]
	v_mfma_f32_16x16x32_bf16 v[18:21], v[192:195], v[240:243], v[18:21]
	v_mfma_f32_16x16x32_bf16 v[10:13], v[184:187], v[248:251], v[10:13]
	v_mfma_f32_16x16x32_bf16 v[2:5], v[192:195], v[248:251], v[2:5]
	s_barrier
	s_add_i32 s57, 0, 0x18000
	v_add_u32_e32 v164, s57, v155
	s_add_i32 s58, 0, 0x1c000
	ds_read_b128 v[142:145], v164
	ds_read_b128 v[168:171], v164 offset:1024
	ds_read_b128 v[172:175], v164 offset:2048
	ds_read_b128 v[176:179], v164 offset:3072
	v_add_u32_e32 v164, s58, v155
	ds_read_b128 v[180:183], v164
	ds_read_b128 v[184:187], v164 offset:1024
	ds_read_b128 v[188:191], v164 offset:2048
	ds_read_b128 v[192:195], v164 offset:3072
	s_add_u32 s36, s36, 0x40000
	s_addc_u32 s37, s37, 0
	s_mov_b32 m0, s50
	v_lshl_add_u64 v[252:253], s[36:37], 0, v[136:137]
	ds_read_b128 v[196:199], v157 offset:32768
	ds_read_b128 v[200:203], v157 offset:33792
	ds_read_b128 v[204:207], v157 offset:34816
	ds_read_b128 v[220:223], v157 offset:35840
	ds_read_b128 v[236:239], v157 offset:36864
	ds_read_b128 v[240:243], v157 offset:37888
	ds_read_b128 v[244:247], v157 offset:38912
	ds_read_b128 v[248:251], v157 offset:39936
	global_load_lds_dwordx4 v[252:253], off
	v_lshl_add_u64 v[252:253], s[36:37], 0, v[132:133]
	s_mov_b32 m0, s51
	s_nop 0
	global_load_lds_dwordx4 v[252:253], off
	s_nop 0
	s_nop 0
	s_nop 0
	s_nop 0
	s_nop 0
	s_nop 0
	s_nop 0
	s_waitcnt vmcnt(8)
	s_waitcnt lgkmcnt(0)
	s_barrier
	s_waitcnt lgkmcnt(0)
	v_mfma_f32_16x16x32_bf16 v[126:129], v[142:145], v[196:199], v[126:129]
	v_mfma_f32_16x16x32_bf16 v[118:121], v[172:175], v[196:199], v[118:121]
	v_mfma_f32_16x16x32_bf16 v[110:113], v[142:145], v[204:207], v[110:113]
	v_mfma_f32_16x16x32_bf16 v[102:105], v[172:175], v[204:207], v[102:105]
	v_mfma_f32_16x16x32_bf16 v[94:97], v[142:145], v[236:239], v[94:97]
	v_mfma_f32_16x16x32_bf16 v[86:89], v[172:175], v[236:239], v[86:89]
	v_mfma_f32_16x16x32_bf16 v[78:81], v[142:145], v[244:247], v[78:81]
	v_mfma_f32_16x16x32_bf16 v[70:73], v[172:175], v[244:247], v[70:73]
	v_mfma_f32_16x16x32_bf16 v[126:129], v[168:171], v[200:203], v[126:129]
	v_mfma_f32_16x16x32_bf16 v[118:121], v[176:179], v[200:203], v[118:121]
	v_mfma_f32_16x16x32_bf16 v[110:113], v[168:171], v[220:223], v[110:113]
	v_mfma_f32_16x16x32_bf16 v[102:105], v[176:179], v[220:223], v[102:105]
	v_mfma_f32_16x16x32_bf16 v[94:97], v[168:171], v[240:243], v[94:97]
	v_mfma_f32_16x16x32_bf16 v[86:89], v[176:179], v[240:243], v[86:89]
	v_mfma_f32_16x16x32_bf16 v[78:81], v[168:171], v[248:251], v[78:81]
	v_mfma_f32_16x16x32_bf16 v[70:73], v[176:179], v[248:251], v[70:73]
	v_mfma_f32_16x16x32_bf16 v[122:125], v[180:183], v[196:199], v[122:125]
	v_mfma_f32_16x16x32_bf16 v[114:117], v[188:191], v[196:199], v[114:117]
	v_mfma_f32_16x16x32_bf16 v[106:109], v[180:183], v[204:207], v[106:109]
	v_mfma_f32_16x16x32_bf16 v[98:101], v[188:191], v[204:207], v[98:101]
	v_mfma_f32_16x16x32_bf16 v[90:93], v[180:183], v[236:239], v[90:93]
	v_mfma_f32_16x16x32_bf16 v[82:85], v[188:191], v[236:239], v[82:85]
	v_mfma_f32_16x16x32_bf16 v[74:77], v[180:183], v[244:247], v[74:77]
	v_mfma_f32_16x16x32_bf16 v[66:69], v[188:191], v[244:247], v[66:69]
	v_mfma_f32_16x16x32_bf16 v[122:125], v[184:187], v[200:203], v[122:125]
	v_mfma_f32_16x16x32_bf16 v[114:117], v[192:195], v[200:203], v[114:117]
	v_mfma_f32_16x16x32_bf16 v[106:109], v[184:187], v[220:223], v[106:109]
	v_mfma_f32_16x16x32_bf16 v[98:101], v[192:195], v[220:223], v[98:101]
	v_mfma_f32_16x16x32_bf16 v[90:93], v[184:187], v[240:243], v[90:93]
	v_mfma_f32_16x16x32_bf16 v[82:85], v[192:195], v[240:243], v[82:85]
	v_mfma_f32_16x16x32_bf16 v[74:77], v[184:187], v[248:251], v[74:77]
	v_mfma_f32_16x16x32_bf16 v[66:69], v[192:195], v[248:251], v[66:69]
	s_barrier
	s_add_i32 s36, s57, s44
	v_lshl_add_u64 v[146:147], v[146:147], 0, s[96:97]
	s_mov_b32 m0, s36
	ds_read_b128 v[196:199], v157 offset:49152
	ds_read_b128 v[200:203], v157 offset:50176
	ds_read_b128 v[204:207], v157 offset:51200
	ds_read_b128 v[220:223], v157 offset:52224
	ds_read_b128 v[236:239], v157 offset:53248
	ds_read_b128 v[240:243], v157 offset:54272
	ds_read_b128 v[244:247], v157 offset:55296
	ds_read_b128 v[248:251], v157 offset:56320
	global_load_lds_dwordx4 v[146:147], off
	s_add_i32 m0, s36, 0x2000
	s_add_u32 s34, s34, 0x40080
	v_lshl_add_u64 v[146:147], v[208:209], 0, s[96:97]
	s_addc_u32 s35, s35, 0
	s_add_i32 s36, s58, s44
	global_load_lds_dwordx4 v[146:147], off
	v_lshl_add_u64 v[146:147], s[34:35], 0, v[134:135]
	s_mov_b32 m0, s36
	s_nop 0
	global_load_lds_dwordx4 v[146:147], off
	v_lshl_add_u64 v[146:147], s[34:35], 0, v[130:131]
	s_add_i32 m0, s36, 0x2000
	s_nop 0
	global_load_lds_dwordx4 v[146:147], off
	v_lshl_add_u64 v[146:147], v[224:225], 0, s[96:97]
	s_mov_b32 m0, s52
	s_nop 0
	global_load_lds_dwordx4 v[146:147], off
	v_lshl_add_u64 v[146:147], v[230:231], 0, s[96:97]
	s_mov_b32 m0, s53
	s_nop 0
	global_load_lds_dwordx4 v[146:147], off
	s_nop 0
	s_nop 0
	s_waitcnt vmcnt(8)
	s_waitcnt lgkmcnt(0)
	s_barrier
	s_waitcnt lgkmcnt(0)
	v_mfma_f32_16x16x32_bf16 v[62:65], v[142:145], v[196:199], v[62:65]
	v_mfma_f32_16x16x32_bf16 v[54:57], v[172:175], v[196:199], v[54:57]
	v_mfma_f32_16x16x32_bf16 v[46:49], v[142:145], v[204:207], v[46:49]
	v_mfma_f32_16x16x32_bf16 v[38:41], v[172:175], v[204:207], v[38:41]
	v_mfma_f32_16x16x32_bf16 v[30:33], v[142:145], v[236:239], v[30:33]
	v_mfma_f32_16x16x32_bf16 v[22:25], v[172:175], v[236:239], v[22:25]
	v_mfma_f32_16x16x32_bf16 v[14:17], v[142:145], v[244:247], v[14:17]
	v_mfma_f32_16x16x32_bf16 v[6:9], v[172:175], v[244:247], v[6:9]
	v_mfma_f32_16x16x32_bf16 v[62:65], v[168:171], v[200:203], v[62:65]
	v_mfma_f32_16x16x32_bf16 v[54:57], v[176:179], v[200:203], v[54:57]
	v_mfma_f32_16x16x32_bf16 v[46:49], v[168:171], v[220:223], v[46:49]
	v_mfma_f32_16x16x32_bf16 v[38:41], v[176:179], v[220:223], v[38:41]
	v_mfma_f32_16x16x32_bf16 v[30:33], v[168:171], v[240:243], v[30:33]
	v_mfma_f32_16x16x32_bf16 v[22:25], v[176:179], v[240:243], v[22:25]
	v_mfma_f32_16x16x32_bf16 v[14:17], v[168:171], v[248:251], v[14:17]
	v_mfma_f32_16x16x32_bf16 v[6:9], v[176:179], v[248:251], v[6:9]
	v_mfma_f32_16x16x32_bf16 v[58:61], v[180:183], v[196:199], v[58:61]
	v_mfma_f32_16x16x32_bf16 v[50:53], v[188:191], v[196:199], v[50:53]
	v_mfma_f32_16x16x32_bf16 v[42:45], v[180:183], v[204:207], v[42:45]
	v_mfma_f32_16x16x32_bf16 v[34:37], v[188:191], v[204:207], v[34:37]
	v_mfma_f32_16x16x32_bf16 v[26:29], v[180:183], v[236:239], v[26:29]
	v_mfma_f32_16x16x32_bf16 v[18:21], v[188:191], v[236:239], v[18:21]
	v_mfma_f32_16x16x32_bf16 v[10:13], v[180:183], v[244:247], v[10:13]
	v_mfma_f32_16x16x32_bf16 v[2:5], v[188:191], v[244:247], v[2:5]
	v_mfma_f32_16x16x32_bf16 v[58:61], v[184:187], v[200:203], v[58:61]
	v_mfma_f32_16x16x32_bf16 v[50:53], v[192:195], v[200:203], v[50:53]
	v_mfma_f32_16x16x32_bf16 v[42:45], v[184:187], v[220:223], v[42:45]
	v_mfma_f32_16x16x32_bf16 v[34:37], v[192:195], v[220:223], v[34:37]
	v_mfma_f32_16x16x32_bf16 v[26:29], v[184:187], v[240:243], v[26:29]
	v_mfma_f32_16x16x32_bf16 v[18:21], v[192:195], v[240:243], v[18:21]
	v_mfma_f32_16x16x32_bf16 v[10:13], v[184:187], v[248:251], v[10:13]
	v_mfma_f32_16x16x32_bf16 v[2:5], v[192:195], v[248:251], v[2:5]
	s_barrier
	s_add_i32 s56, s56, 2
	s_add_u32 s41, s41, 0x100
	s_addc_u32 s43, s43, 0
	s_add_u32 s30, s30, 0x100
	s_addc_u32 s31, s31, 0
	s_cmp_gt_u32 s56, 13

.LBB0_639:
	s_ashr_i32 s13, s12, 31
	s_lshl_b64 s[14:15], s[12:13], 19
	s_add_u32 s14, s80, s14
	s_addc_u32 s15, s81, s15
	s_and_b64 s[16:17], s[4:5], exec
	s_cselect_b32 s13, s15, s23
	s_cselect_b32 s19, s14, s22
	s_ashr_i32 s11, s10, 31
	s_lshl_b64 s[16:17], s[10:11], 19
	s_add_u32 s16, s26, s16
	s_addc_u32 s17, s27, s17
	s_and_b64 s[24:25], s[4:5], exec
	s_cselect_b32 s11, s17, s21
	s_cselect_b32 s41, s16, s20
	s_add_u32 s43, s20, 0x100
	s_addc_u32 s44, s21, 0
	s_add_u32 s20, s22, 0x40080
	s_addc_u32 s21, s23, 0
	s_mov_b32 s45, -2
	s_add_u32 s22, s20, 0xfffc0080
	s_addc_u32 s23, s21, -1
	s_add_i32 s46, 0, 0x10000
	s_cmp_eq_u32 s45, 12
	s_cselect_b32 s25, s13, s23
	s_cselect_b32 s24, s19, s22
	v_add_u32_e32 v150, s46, v159
	s_cselect_b32 s23, s11, s44
	s_cselect_b32 s22, s41, s43
	s_add_i32 s48, 0, 0x14000
	ds_read_b128 v[164:167], v150
	ds_read_b128 v[168:171], v150 offset:1024
	ds_read_b128 v[172:175], v150 offset:2048
	ds_read_b128 v[176:179], v150 offset:3072
	v_add_u32_e32 v150, s48, v159
	ds_read_b128 v[180:183], v150
	ds_read_b128 v[184:187], v150 offset:1024
	ds_read_b128 v[188:191], v150 offset:2048
	ds_read_b128 v[192:195], v150 offset:3072
	v_lshl_add_u64 v[150:151], s[20:21], 0, v[140:141]
	s_add_i32 m0, s30, 0xc000
	ds_read_b128 v[196:199], v162
	ds_read_b128 v[200:203], v162 offset:1024
	ds_read_b128 v[204:207], v162 offset:2048
	ds_read_b128 v[220:223], v162 offset:3072
	ds_read_b128 v[236:239], v162 offset:4096
	ds_read_b128 v[240:243], v162 offset:5120
	ds_read_b128 v[244:247], v162 offset:6144
	ds_read_b128 v[248:251], v162 offset:7168
	global_load_lds_dwordx4 v[150:151], off
	v_lshl_add_u64 v[150:151], s[20:21], 0, v[138:139]
	s_add_i32 m0, s30, 0xe000
	s_nop 0
	global_load_lds_dwordx4 v[150:151], off
	s_nop 0
	s_nop 0
	s_nop 0
	s_nop 0
	s_nop 0
	s_nop 0
	s_nop 0
	s_nop 0
	s_nop 0
	s_nop 0
	s_nop 0
	s_nop 0
	s_nop 0
	s_nop 0
	s_nop 0
	s_nop 0
	s_nop 0
	s_nop 0
	s_nop 0
	s_nop 0
	s_cmp_eq_u32 s39, 1
	s_cbranch_scc1 .Lci_fw0
	s_waitcnt vmcnt(16)
	s_branch .Lci_fj0

.Lci_fj0:
	s_waitcnt lgkmcnt(0)
	s_barrier
	s_waitcnt lgkmcnt(0)
	v_mfma_f32_16x16x32_bf16 v[126:129], v[164:167], v[196:199], 0
	v_mfma_f32_16x16x32_bf16 v[122:125], v[172:175], v[196:199], 0
	v_mfma_f32_16x16x32_bf16 v[118:121], v[164:167], v[204:207], 0
	v_mfma_f32_16x16x32_bf16 v[114:117], v[172:175], v[204:207], 0
	v_mfma_f32_16x16x32_bf16 v[110:113], v[164:167], v[236:239], 0
	v_mfma_f32_16x16x32_bf16 v[106:109], v[172:175], v[236:239], 0
	v_mfma_f32_16x16x32_bf16 v[102:105], v[164:167], v[244:247], 0
	v_mfma_f32_16x16x32_bf16 v[98:101], v[172:175], v[244:247], 0
	v_mfma_f32_16x16x32_bf16 v[126:129], v[168:171], v[200:203], v[126:129]
	v_mfma_f32_16x16x32_bf16 v[122:125], v[176:179], v[200:203], v[122:125]
	v_mfma_f32_16x16x32_bf16 v[118:121], v[168:171], v[220:223], v[118:121]
	v_mfma_f32_16x16x32_bf16 v[114:117], v[176:179], v[220:223], v[114:117]
	v_mfma_f32_16x16x32_bf16 v[110:113], v[168:171], v[240:243], v[110:113]
	v_mfma_f32_16x16x32_bf16 v[106:109], v[176:179], v[240:243], v[106:109]
	v_mfma_f32_16x16x32_bf16 v[102:105], v[168:171], v[248:251], v[102:105]
	v_mfma_f32_16x16x32_bf16 v[98:101], v[176:179], v[248:251], v[98:101]
	v_mfma_f32_16x16x32_bf16 v[94:97], v[180:183], v[196:199], 0
	v_mfma_f32_16x16x32_bf16 v[90:93], v[188:191], v[196:199], 0
	v_mfma_f32_16x16x32_bf16 v[86:89], v[180:183], v[204:207], 0
	v_mfma_f32_16x16x32_bf16 v[82:85], v[188:191], v[204:207], 0
	v_mfma_f32_16x16x32_bf16 v[78:81], v[180:183], v[236:239], 0
	v_mfma_f32_16x16x32_bf16 v[74:77], v[188:191], v[236:239], 0
	v_mfma_f32_16x16x32_bf16 v[70:73], v[180:183], v[244:247], 0
	v_mfma_f32_16x16x32_bf16 v[66:69], v[188:191], v[244:247], 0
	v_mfma_f32_16x16x32_bf16 v[94:97], v[184:187], v[200:203], v[94:97]
	v_mfma_f32_16x16x32_bf16 v[90:93], v[192:195], v[200:203], v[90:93]
	v_mfma_f32_16x16x32_bf16 v[86:89], v[184:187], v[220:223], v[86:89]
	v_mfma_f32_16x16x32_bf16 v[82:85], v[192:195], v[220:223], v[82:85]
	v_mfma_f32_16x16x32_bf16 v[78:81], v[184:187], v[240:243], v[78:81]
	v_mfma_f32_16x16x32_bf16 v[74:77], v[192:195], v[240:243], v[74:77]
	v_mfma_f32_16x16x32_bf16 v[70:73], v[184:187], v[248:251], v[70:73]
	v_mfma_f32_16x16x32_bf16 v[66:69], v[192:195], v[248:251], v[66:69]
	s_barrier
	s_add_i32 s46, s46, s28
	v_lshl_add_u64 v[150:151], s[22:23], 0, v[134:135]
	s_mov_b32 m0, s46
	ds_read_b128 v[196:199], v162 offset:16384
	ds_read_b128 v[200:203], v162 offset:17408
	ds_read_b128 v[204:207], v162 offset:18432
	ds_read_b128 v[220:223], v162 offset:19456
	ds_read_b128 v[236:239], v162 offset:20480
	ds_read_b128 v[240:243], v162 offset:21504
	ds_read_b128 v[244:247], v162 offset:22528
	ds_read_b128 v[248:251], v162 offset:23552
	global_load_lds_dwordx4 v[150:151], off
	s_add_i32 m0, s46, 0x2000
	s_add_u32 s46, s22, 0x40000
	v_lshl_add_u64 v[208:209], s[22:23], 0, v[130:131]
	s_addc_u32 s47, s23, 0
	s_add_i32 s48, s48, s28
	global_load_lds_dwordx4 v[208:209], off
	v_lshl_add_u64 v[224:225], s[46:47], 0, v[134:135]
	s_mov_b32 m0, s48
	v_lshl_add_u64 v[252:253], s[24:25], 0, v[132:133]
	global_load_lds_dwordx4 v[224:225], off
	v_lshl_add_u64 v[224:225], s[46:47], 0, v[130:131]
	s_add_i32 m0, s48, 0x2000
	s_nop 0
	global_load_lds_dwordx4 v[224:225], off
	v_lshl_add_u64 v[224:225], s[24:25], 0, v[136:137]
	s_mov_b32 m0, s30
	s_nop 0
	global_load_lds_dwordx4 v[224:225], off
	s_mov_b32 m0, s31
	s_nop 0
	global_load_lds_dwordx4 v[252:253], off
	s_nop 0
	s_nop 0
	s_nop 0
	s_nop 0
	s_nop 0
	s_nop 0
	s_nop 0
	s_nop 0
	s_nop 0
	s_nop 0
	s_nop 0
	s_nop 0
	s_nop 0
	s_nop 0
	s_nop 0
	s_cmp_eq_u32 s39, 1
	s_cbranch_scc1 .Lci_fw1
	s_waitcnt vmcnt(16)
	s_branch .Lci_fj1

.Lci_fj1:
	s_waitcnt lgkmcnt(0)
	s_barrier
	s_waitcnt lgkmcnt(0)
	v_mfma_f32_16x16x32_bf16 v[62:65], v[164:167], v[196:199], 0
	v_mfma_f32_16x16x32_bf16 v[58:61], v[172:175], v[196:199], 0
	v_mfma_f32_16x16x32_bf16 v[54:57], v[164:167], v[204:207], 0
	v_mfma_f32_16x16x32_bf16 v[50:53], v[172:175], v[204:207], 0
	v_mfma_f32_16x16x32_bf16 v[46:49], v[164:167], v[236:239], 0
	v_mfma_f32_16x16x32_bf16 v[42:45], v[172:175], v[236:239], 0
	v_mfma_f32_16x16x32_bf16 v[38:41], v[164:167], v[244:247], 0
	v_mfma_f32_16x16x32_bf16 v[34:37], v[172:175], v[244:247], 0
	v_mfma_f32_16x16x32_bf16 v[62:65], v[168:171], v[200:203], v[62:65]
	v_mfma_f32_16x16x32_bf16 v[58:61], v[176:179], v[200:203], v[58:61]
	v_mfma_f32_16x16x32_bf16 v[54:57], v[168:171], v[220:223], v[54:57]
	v_mfma_f32_16x16x32_bf16 v[50:53], v[176:179], v[220:223], v[50:53]
	v_mfma_f32_16x16x32_bf16 v[46:49], v[168:171], v[240:243], v[46:49]
	v_mfma_f32_16x16x32_bf16 v[42:45], v[176:179], v[240:243], v[42:45]
	v_mfma_f32_16x16x32_bf16 v[38:41], v[168:171], v[248:251], v[38:41]
	v_mfma_f32_16x16x32_bf16 v[34:37], v[176:179], v[248:251], v[34:37]
	v_mfma_f32_16x16x32_bf16 v[30:33], v[180:183], v[196:199], 0
	v_mfma_f32_16x16x32_bf16 v[26:29], v[188:191], v[196:199], 0
	v_mfma_f32_16x16x32_bf16 v[22:25], v[180:183], v[204:207], 0
	v_mfma_f32_16x16x32_bf16 v[18:21], v[188:191], v[204:207], 0
	v_mfma_f32_16x16x32_bf16 v[14:17], v[180:183], v[236:239], 0
	v_mfma_f32_16x16x32_bf16 v[10:13], v[188:191], v[236:239], 0
	v_mfma_f32_16x16x32_bf16 v[6:9], v[180:183], v[244:247], 0
	v_mfma_f32_16x16x32_bf16 v[2:5], v[188:191], v[244:247], 0
	v_mfma_f32_16x16x32_bf16 v[30:33], v[184:187], v[200:203], v[30:33]
	v_mfma_f32_16x16x32_bf16 v[26:29], v[192:195], v[200:203], v[26:29]
	v_mfma_f32_16x16x32_bf16 v[22:25], v[184:187], v[220:223], v[22:25]
	v_mfma_f32_16x16x32_bf16 v[18:21], v[192:195], v[220:223], v[18:21]
	v_mfma_f32_16x16x32_bf16 v[14:17], v[184:187], v[240:243], v[14:17]
	v_mfma_f32_16x16x32_bf16 v[10:13], v[192:195], v[240:243], v[10:13]
	v_mfma_f32_16x16x32_bf16 v[6:9], v[184:187], v[248:251], v[6:9]
	v_mfma_f32_16x16x32_bf16 v[2:5], v[192:195], v[248:251], v[2:5]
	s_barrier
	s_add_i32 s46, 0, 0x18000
	v_add_u32_e32 v163, s46, v159
	s_add_i32 s47, 0, 0x1c000
	ds_read_b128 v[164:167], v163
	ds_read_b128 v[168:171], v163 offset:1024
	ds_read_b128 v[172:175], v163 offset:2048
	ds_read_b128 v[176:179], v163 offset:3072
	v_add_u32_e32 v163, s47, v159
	ds_read_b128 v[180:183], v163
	ds_read_b128 v[184:187], v163 offset:1024
	ds_read_b128 v[188:191], v163 offset:2048
	ds_read_b128 v[192:195], v163 offset:3072
	s_add_u32 s24, s24, 0x40000
	s_addc_u32 s25, s25, 0
	s_mov_b32 m0, s34
	v_lshl_add_u64 v[230:231], s[24:25], 0, v[136:137]
	ds_read_b128 v[196:199], v162 offset:32768
	ds_read_b128 v[200:203], v162 offset:33792
	ds_read_b128 v[204:207], v162 offset:34816
	ds_read_b128 v[220:223], v162 offset:35840
	ds_read_b128 v[236:239], v162 offset:36864
	ds_read_b128 v[240:243], v162 offset:37888
	ds_read_b128 v[244:247], v162 offset:38912
	ds_read_b128 v[248:251], v162 offset:39936
	global_load_lds_dwordx4 v[230:231], off
	v_lshl_add_u64 v[230:231], s[24:25], 0, v[132:133]
	s_mov_b32 m0, s35
	s_nop 0
	global_load_lds_dwordx4 v[230:231], off
	s_nop 0
	s_nop 0
	s_nop 0
	s_nop 0
	s_nop 0
	s_nop 0
	s_nop 0
	s_waitcnt vmcnt(8)
	s_waitcnt lgkmcnt(0)
	s_barrier
	s_waitcnt lgkmcnt(0)
	v_mfma_f32_16x16x32_bf16 v[126:129], v[164:167], v[196:199], v[126:129]
	v_mfma_f32_16x16x32_bf16 v[122:125], v[172:175], v[196:199], v[122:125]
	v_mfma_f32_16x16x32_bf16 v[118:121], v[164:167], v[204:207], v[118:121]
	v_mfma_f32_16x16x32_bf16 v[114:117], v[172:175], v[204:207], v[114:117]
	v_mfma_f32_16x16x32_bf16 v[110:113], v[164:167], v[236:239], v[110:113]
	v_mfma_f32_16x16x32_bf16 v[106:109], v[172:175], v[236:239], v[106:109]
	v_mfma_f32_16x16x32_bf16 v[102:105], v[164:167], v[244:247], v[102:105]
	v_mfma_f32_16x16x32_bf16 v[98:101], v[172:175], v[244:247], v[98:101]
	v_mfma_f32_16x16x32_bf16 v[126:129], v[168:171], v[200:203], v[126:129]
	v_mfma_f32_16x16x32_bf16 v[122:125], v[176:179], v[200:203], v[122:125]
	v_mfma_f32_16x16x32_bf16 v[118:121], v[168:171], v[220:223], v[118:121]
	v_mfma_f32_16x16x32_bf16 v[114:117], v[176:179], v[220:223], v[114:117]
	v_mfma_f32_16x16x32_bf16 v[110:113], v[168:171], v[240:243], v[110:113]
	v_mfma_f32_16x16x32_bf16 v[106:109], v[176:179], v[240:243], v[106:109]
	v_mfma_f32_16x16x32_bf16 v[102:105], v[168:171], v[248:251], v[102:105]
	v_mfma_f32_16x16x32_bf16 v[98:101], v[176:179], v[248:251], v[98:101]
	v_mfma_f32_16x16x32_bf16 v[94:97], v[180:183], v[196:199], v[94:97]
	v_mfma_f32_16x16x32_bf16 v[90:93], v[188:191], v[196:199], v[90:93]
	v_mfma_f32_16x16x32_bf16 v[86:89], v[180:183], v[204:207], v[86:89]
	v_mfma_f32_16x16x32_bf16 v[82:85], v[188:191], v[204:207], v[82:85]
	v_mfma_f32_16x16x32_bf16 v[78:81], v[180:183], v[236:239], v[78:81]
	v_mfma_f32_16x16x32_bf16 v[74:77], v[188:191], v[236:239], v[74:77]
	v_mfma_f32_16x16x32_bf16 v[70:73], v[180:183], v[244:247], v[70:73]
	v_mfma_f32_16x16x32_bf16 v[66:69], v[188:191], v[244:247], v[66:69]
	v_mfma_f32_16x16x32_bf16 v[94:97], v[184:187], v[200:203], v[94:97]
	v_mfma_f32_16x16x32_bf16 v[90:93], v[192:195], v[200:203], v[90:93]
	v_mfma_f32_16x16x32_bf16 v[86:89], v[184:187], v[220:223], v[86:89]
	v_mfma_f32_16x16x32_bf16 v[82:85], v[192:195], v[220:223], v[82:85]
	v_mfma_f32_16x16x32_bf16 v[78:81], v[184:187], v[240:243], v[78:81]
	v_mfma_f32_16x16x32_bf16 v[74:77], v[192:195], v[240:243], v[74:77]
	v_mfma_f32_16x16x32_bf16 v[70:73], v[184:187], v[248:251], v[70:73]
	v_mfma_f32_16x16x32_bf16 v[66:69], v[192:195], v[248:251], v[66:69]
	s_barrier
	s_add_i32 s24, s46, s28
	v_lshl_add_u64 v[150:151], v[150:151], 0, s[96:97]
	s_mov_b32 m0, s24
	ds_read_b128 v[196:199], v162 offset:49152
	ds_read_b128 v[200:203], v162 offset:50176
	ds_read_b128 v[204:207], v162 offset:51200
	ds_read_b128 v[220:223], v162 offset:52224
	ds_read_b128 v[236:239], v162 offset:53248
	ds_read_b128 v[240:243], v162 offset:54272
	ds_read_b128 v[244:247], v162 offset:55296
	ds_read_b128 v[248:251], v162 offset:56320
	global_load_lds_dwordx4 v[150:151], off
	s_add_i32 m0, s24, 0x2000
	s_add_u32 s22, s22, 0x40080
	v_lshl_add_u64 v[150:151], v[208:209], 0, s[96:97]
	s_addc_u32 s23, s23, 0
	s_add_i32 s24, s47, s28
	global_load_lds_dwordx4 v[150:151], off
	v_lshl_add_u64 v[150:151], s[22:23], 0, v[134:135]
	s_mov_b32 m0, s24
	s_nop 0
	global_load_lds_dwordx4 v[150:151], off
	v_lshl_add_u64 v[150:151], s[22:23], 0, v[130:131]
	s_add_i32 m0, s24, 0x2000
	s_nop 0
	global_load_lds_dwordx4 v[150:151], off
	v_lshl_add_u64 v[150:151], v[224:225], 0, s[96:97]
	s_mov_b32 m0, s36
	s_nop 0
	global_load_lds_dwordx4 v[150:151], off
	v_lshl_add_u64 v[150:151], v[252:253], 0, s[96:97]
	s_mov_b32 m0, s37
	s_nop 0
	global_load_lds_dwordx4 v[150:151], off
	s_nop 0
	s_nop 0
	s_waitcnt vmcnt(8)
	s_waitcnt lgkmcnt(0)
	s_barrier
	s_waitcnt lgkmcnt(0)
	v_mfma_f32_16x16x32_bf16 v[62:65], v[164:167], v[196:199], v[62:65]
	v_mfma_f32_16x16x32_bf16 v[58:61], v[172:175], v[196:199], v[58:61]
	v_mfma_f32_16x16x32_bf16 v[54:57], v[164:167], v[204:207], v[54:57]
	v_mfma_f32_16x16x32_bf16 v[50:53], v[172:175], v[204:207], v[50:53]
	v_mfma_f32_16x16x32_bf16 v[46:49], v[164:167], v[236:239], v[46:49]
	v_mfma_f32_16x16x32_bf16 v[42:45], v[172:175], v[236:239], v[42:45]
	v_mfma_f32_16x16x32_bf16 v[38:41], v[164:167], v[244:247], v[38:41]
	v_mfma_f32_16x16x32_bf16 v[34:37], v[172:175], v[244:247], v[34:37]
	v_mfma_f32_16x16x32_bf16 v[62:65], v[168:171], v[200:203], v[62:65]
	v_mfma_f32_16x16x32_bf16 v[58:61], v[176:179], v[200:203], v[58:61]
	v_mfma_f32_16x16x32_bf16 v[54:57], v[168:171], v[220:223], v[54:57]
	v_mfma_f32_16x16x32_bf16 v[50:53], v[176:179], v[220:223], v[50:53]
	v_mfma_f32_16x16x32_bf16 v[46:49], v[168:171], v[240:243], v[46:49]
	v_mfma_f32_16x16x32_bf16 v[42:45], v[176:179], v[240:243], v[42:45]
	v_mfma_f32_16x16x32_bf16 v[38:41], v[168:171], v[248:251], v[38:41]
	v_mfma_f32_16x16x32_bf16 v[34:37], v[176:179], v[248:251], v[34:37]
	v_mfma_f32_16x16x32_bf16 v[30:33], v[180:183], v[196:199], v[30:33]
	v_mfma_f32_16x16x32_bf16 v[26:29], v[188:191], v[196:199], v[26:29]
	v_mfma_f32_16x16x32_bf16 v[22:25], v[180:183], v[204:207], v[22:25]
	v_mfma_f32_16x16x32_bf16 v[18:21], v[188:191], v[204:207], v[18:21]
	v_mfma_f32_16x16x32_bf16 v[14:17], v[180:183], v[236:239], v[14:17]
	v_mfma_f32_16x16x32_bf16 v[10:13], v[188:191], v[236:239], v[10:13]
	v_mfma_f32_16x16x32_bf16 v[6:9], v[180:183], v[244:247], v[6:9]
	v_mfma_f32_16x16x32_bf16 v[2:5], v[188:191], v[244:247], v[2:5]
	v_mfma_f32_16x16x32_bf16 v[30:33], v[184:187], v[200:203], v[30:33]
	v_mfma_f32_16x16x32_bf16 v[26:29], v[192:195], v[200:203], v[26:29]
	v_mfma_f32_16x16x32_bf16 v[22:25], v[184:187], v[220:223], v[22:25]
	v_mfma_f32_16x16x32_bf16 v[18:21], v[192:195], v[220:223], v[18:21]
	v_mfma_f32_16x16x32_bf16 v[14:17], v[184:187], v[240:243], v[14:17]
	v_mfma_f32_16x16x32_bf16 v[10:13], v[192:195], v[240:243], v[10:13]
	v_mfma_f32_16x16x32_bf16 v[6:9], v[184:187], v[248:251], v[6:9]
	v_mfma_f32_16x16x32_bf16 v[2:5], v[192:195], v[248:251], v[2:5]
	s_barrier
	s_add_i32 s45, s45, 2
	s_add_u32 s43, s43, 0x100
	s_addc_u32 s44, s44, 0
	s_add_u32 s20, s20, 0x100
	s_addc_u32 s21, s21, 0
	s_cmp_gt_u32 s45, 13
